# code placement: 12 B of s_nop in the cold phase-8 entry so the MLP-up GEMM K-loop head sits at the baseline's byte phase (mod 64 = 32 instead of 20)
# baseline (speedup 1.0000x reference)
; #define PG8_STAGE(bufoff, gbase, voff) do { _Pragma("unroll") for (int _i = 0; _i < 2; ++_i) \
;         __builtin_amdgcn_global_load_lds((const unsigned*)((const char*)(gbase) + (voff)[_i]), (PG8_LAS unsigned*)(lds + (bufoff) + ldsw + _i * 8192), 16, 0, 0); } while (0)
; #define PG8_BAR __builtin_amdgcn_s_barrier()
; template <class Epi, class Sched, bool ALIGN_EPI = false, bool SP2 = false, bool UNIFORM_NT = false>
; __device__ __forceinline__ void gemm_phase(PG8_LAS unsigned char* lds, const Gemm g, const Sched& S, const Epi& E, int tid_in) {
;     int tid_o = tid_in; asm volatile("" : "+v"(tid_o)); const int tid = tid_o, wid = __builtin_amdgcn_readfirstlane(tid >> 6), lane = tid & 63, wr = wid >> 2, wc = wid & 3, fr = lane & 15, fq = lane >> 4;
;     const int lda = g.lda, ldb = g.ldb; const int nt_uniform = g.K / BK;
;     unsigned voffA[2], voffB[2];
; #pragma unroll
;     for (int i = 0; i < 2; ++i) { int R, C; stage_rc(tid * 16 + i * 8192, R, C); const int Rb = Epi::PERM ? ((R & ~31) + perm32(R & 31)) : R;
;         voffA[i] = (unsigned)(R * lda + C) * 2u; voffB[i] = (unsigned)(Rb * ldb + C) * 2u; }
;     const size_t kstep = (size_t)(BK * 2);
;     const size_t hstepA = (size_t)HALF * lda * 2, hstepB = (size_t)HALF * ldb * 2;
;     const size_t tstepA = 2 * hstepA, tstepB = 2 * hstepB;
;     const unsigned ldsw = (unsigned)wid * 1024u;
;     const int aoff = lds_byte(wr * 64 + fr, fq * 8), boff = lds_byte(wc * 32 + fr, fq * 8);
;     ...
;     Unit cur, nxt; int ui = 0;
;     if (!S.next(0, cur)) return;
;     f32x4 acc[2][2][4][2];
; #pragma unroll
;     for (int a = 0; a < 2; ++a)
; #pragma unroll
;         for (int b = 0; b < 2; ++b)
; #pragma unroll
;             for (int m = 0; m < 4; ++m)
; #pragma unroll
;                 for (int n = 0; n < 2; ++n) acc[a][b][m][n] = (f32x4){0.f, 0.f, 0.f, 0.f};
;     bf16x8 At[4][2], B0[2][2], B1[2][2];
;     const char* cA = (const char*)g.A + (size_t)cur.pm * tstepA + (size_t)cur.kofs * 2; const char* cB = (const char*)g.Bt + (size_t)cur.pn * tstepB + (size_t)cur.kofs * 2;
;     S.a_ready(cur);
;     if constexpr (SP2) {
;         PG8_STAGE(PG8_SB(0, 0), cB, voffB); PG8_STAGE(PG8_SB(0, 1), cB + hstepB, voffB); PG8_STAGE(PG8_SA(0, 0), cA, voffA); PG8_STAGE(PG8_SA(0, 1), cA + hstepA, voffA);
;         if (wr == 1) PG8_BAR;
.LBB0_824:
	s_nop 0
	s_nop 0
	s_nop 0
	v_readlane_b32 s0, v252, 6
	v_mbcnt_lo_u32_b32 v0, -1, 0
	v_mbcnt_hi_u32_b32 v0, -1, v0
	v_readlane_b32 s1, v252, 7
	v_add_u32_e32 v8, s64, v0
	s_andn2_b64 vcc, exec, s[0:1]
	v_readfirstlane_b32 s4, v8
	s_cbranch_vccnz .LBB0_840
	v_lshlrev_b32_e32 v0, 4, v8
	s_waitcnt vmcnt(0)
	v_add_u32_e32 v3, 0x2000, v0
	v_ashrrev_i32_e32 v2, 31, v3
	v_lshrrev_b32_e32 v2, 22, v2
	v_add_u32_e32 v2, v3, v2
	v_ashrrev_i32_e32 v2, 10, v2
	v_mul_i32_i24_e32 v4, 0x400, v2
	v_sub_u32_e32 v3, v3, v4
	v_lshrrev_b32_e32 v4, 4, v3
	v_bitop3_b32 v4, v4, v3, 32 bitop3:0x6c
	v_ashrrev_i32_e32 v3, 31, v4
	v_lshrrev_b32_e32 v3, 26, v3
	s_ashr_i32 s5, s4, 6
	v_add_u32_e32 v5, v4, v3
	v_lshlrev_b32_e32 v6, 3, v2
	s_ashr_i32 s10, s4, 8
	s_lshl_b32 s3, s5, 10
	v_ashrrev_i32_e32 v3, 6, v5
	v_and_b32_e32 v6, -16, v6
	s_add_u32 s6, s95, 0x200000
	v_readlane_b32 s0, v254, 38
	v_add_u32_e32 v6, v3, v6
	s_addc_u32 s7, s0, 0
	v_and_b32_e32 v7, 3, v3
	s_mov_b32 s0, 0x1fffe0
	v_lshrrev_b32_e32 v9, 2, v6
	v_lshlrev_b32_e32 v10, 1, v6
	v_and_b32_e32 v5, 0xc0, v5
	v_and_or_b32 v7, v6, s0, v7
	v_and_b32_e32 v9, 4, v9
	v_and_b32_e32 v10, 24, v10
	v_sub_u32_e32 v4, v4, v5
	v_mov_b32_e32 v13, 1
	v_or3_b32 v7, v7, v9, v10
	v_lshlrev_b32_e32 v9, 5, v2
	v_ashrrev_i16_sdwa v4, v13, sext(v4) dst_sel:DWORD dst_unused:UNUSED_PAD src0_sel:DWORD src1_sel:BYTE_0
	v_and_b32_e32 v9, 32, v9
	v_bfe_i32 v4, v4, 0, 16
	v_add_lshl_u32 v5, v9, v4, 1
	v_lshl_add_u32 v130, v7, 11, v5
	v_lshl_add_u32 v132, v6, 11, v5
	v_bfe_i32 v5, v8, 27, 1
	v_lshrrev_b32_e32 v5, 22, v5
	v_add_u32_e32 v5, v0, v5
	v_and_b32_e32 v5, 0xfffffc00, v5
	v_sub_u32_e32 v0, v0, v5
	v_lshrrev_b32_e32 v5, 4, v0
	v_ashrrev_i32_e32 v6, 31, v8
	v_bitop3_b32 v0, v5, v0, 32 bitop3:0x6c
	v_lshrrev_b32_e32 v6, 26, v6
	v_ashrrev_i32_e32 v5, 31, v0
	v_add_u32_e32 v6, v8, v6
	v_lshrrev_b32_e32 v5, 26, v5
	v_ashrrev_i32_e32 v6, 6, v6
	v_add_u32_e32 v7, v0, v5
	v_lshlrev_b32_e32 v9, 3, v6
	v_ashrrev_i32_e32 v5, 6, v7
	v_and_b32_e32 v9, -16, v9
	v_add_u32_e32 v9, v5, v9
	v_and_b32_e32 v10, 3, v5
	v_lshrrev_b32_e32 v11, 2, v9
	v_lshlrev_b32_e32 v12, 1, v9
	v_and_b32_e32 v7, 0xc0, v7
	v_and_or_b32 v10, v9, s0, v10
	v_and_b32_e32 v11, 4, v11
	v_and_b32_e32 v12, 24, v12
	v_sub_u32_e32 v0, v0, v7
	v_or3_b32 v10, v10, v11, v12
	v_lshlrev_b32_e32 v11, 5, v6
	v_ashrrev_i16_sdwa v0, v13, sext(v0) dst_sel:DWORD dst_unused:UNUSED_PAD src0_sel:DWORD src1_sel:BYTE_0
	v_readlane_b32 s0, v253, 6
	v_and_b32_e32 v11, 32, v11
	v_bfe_i32 v7, v0, 0, 16
	v_readlane_b32 s1, v253, 7
	s_add_u32 s26, s6, s0
	v_add_lshl_u32 v11, v11, v7, 1
	s_addc_u32 s27, s7, s1
	s_add_i32 s8, s3, 0
	v_lshl_add_u32 v0, v10, 11, v11
	s_add_i32 m0, s8, 0x10000
	v_readlane_b32 s0, v253, 15
	global_load_lds_dwordx4 v0, s[26:27]
	s_add_i32 m0, s8, 0x12000
	v_readlane_b32 s1, v253, 16
	s_add_u32 s24, s96, s0
	s_addc_u32 s25, s97, s1
	s_add_u32 s0, s26, 0x40000
	global_load_lds_dwordx4 v130, s[26:27]
	s_addc_u32 s1, s27, 0
	s_add_i32 m0, s8, 0x14000
	s_add_i32 s9, s8, 0x2000
	global_load_lds_dwordx4 v0, s[0:1]
	s_add_i32 m0, s8, 0x16000
	v_lshl_add_u32 v134, v9, 11, v11
	global_load_lds_dwordx4 v130, s[0:1]
	s_mov_b32 m0, s8
	s_add_u32 s0, s24, 0x40000
	global_load_lds_dwordx4 v134, s[24:25]
	s_mov_b32 m0, s9
	s_addc_u32 s1, s25, 0
	s_add_i32 s14, s8, 0x4000
	global_load_lds_dwordx4 v132, s[24:25]
	s_mov_b32 m0, s14
	s_add_i32 s15, s8, 0x6000
	global_load_lds_dwordx4 v134, s[0:1]
	s_mov_b32 m0, s15
	s_cmp_eq_u32 s10, 1
	global_load_lds_dwordx4 v132, s[0:1]
	s_cselect_b64 s[0:1], -1, 0
	s_cmp_lg_u32 s10, 1
	s_cbranch_scc1 .LBB0_827
	s_barrier
